# attention loop: V fragment reads for the first two remaining PV MFMAs issued in the QK section into spare registers (longer LDS prefetch distance)
# baseline (speedup 1.0000x reference)
.LBB0_1326:
	s_mul_hi_u32 s34, s77, 0xaaaaaaab
	s_lshr_b32 s34, s34, 1
	s_mul_i32 s34, s34, 0xc000
	v_subrev_u32_e32 v0, s34, v130
	s_add_i32 s34, s2, s36
	v_add_u32_e32 v0, s34, v0
	ds_read_b128 v[188:191], v0
	ds_read_b128 v[82:85], v0 offset:4096
	ds_read_b128 v[94:97], v0 offset:6144
	ds_read_b128 v[98:101], v0 offset:1024
	ds_read_b128 v[86:89], v0 offset:2048
	ds_read_b128 v[132:135], v0 offset:3072
	s_waitcnt lgkmcnt(9)
	v_mfma_f32_16x16x32_bf16 v[30:33], v[204:207], v[14:17], v[30:33]
	s_waitcnt lgkmcnt(8)
	v_mfma_f32_16x16x32_bf16 v[50:53], v[208:211], v[14:17], v[50:53]
	s_waitcnt lgkmcnt(7)
	v_mfma_f32_16x16x32_bf16 v[42:45], v[212:215], v[14:17], v[42:45]
	s_waitcnt lgkmcnt(6)
	v_mfma_f32_16x16x32_bf16 v[34:37], v[216:219], v[14:17], v[34:37]
	s_waitcnt lgkmcnt(5)
	v_mfma_f32_16x16x32_bf16 v[188:191], v[188:191], v[10:13], v[150:153]
	ds_read_b128 v[78:81], v0 offset:5120
	ds_read_b128 v[220:223], v131 offset:57344
	s_waitcnt lgkmcnt(3)
	v_mfma_f32_16x16x32_bf16 v[136:139], v[86:89], v[10:13], v[150:153]
	ds_read_b128 v[86:89], v0 offset:7168
	ds_read_b128 v[140:143], v131 offset:59392
	v_mfma_f32_16x16x32_bf16 v[90:93], v[82:85], v[10:13], v[150:153]
	v_mfma_f32_16x16x32_bf16 v[94:97], v[94:97], v[10:13], v[150:153]
	v_mfma_f32_16x16x32_bf16 v[160:163], v[98:101], v[18:21], v[188:191]
	s_waitcnt lgkmcnt(4)
	v_mfma_f32_16x16x32_bf16 v[164:167], v[132:135], v[18:21], v[136:139]
	s_mov_b32 s34, 0x41000000
	v_cmp_lt_f32_e32 vcc, s34, v194
	s_cmp_lg_u64 vcc, 0
	s_cselect_b64 s[34:35], -1, 0
	s_cbranch_vccz .LBB0_1328
	v_cndmask_b32_e32 v132, 0, v194, vcc
	v_exp_f32_e64 v0, -v132
	v_sub_f32_e32 v74, v74, v132
	v_sub_f32_e32 v75, v75, v132
	v_sub_f32_e32 v76, v76, v132
	v_sub_f32_e32 v77, v77, v132
	v_sub_f32_e32 v70, v70, v132
	v_sub_f32_e32 v71, v71, v132
	v_sub_f32_e32 v72, v72, v132
	v_sub_f32_e32 v73, v73, v132
	v_sub_f32_e32 v22, v22, v132
	v_sub_f32_e32 v23, v23, v132
	v_sub_f32_e32 v24, v24, v132
	v_sub_f32_e32 v25, v25, v132
	v_sub_f32_e32 v26, v26, v132
	v_sub_f32_e32 v27, v27, v132
	v_sub_f32_e32 v28, v28, v132
	v_sub_f32_e32 v29, v29, v132
	v_add_f32_e32 v113, v113, v132
	v_xor_b32_e32 v150, 0x80000000, v113
	v_mov_b32_e32 v151, v150
	v_mov_b32_e32 v152, v150
	v_mov_b32_e32 v153, v150
	s_branch .LBB0_1329
.LBB0_1328:
.LBB0_1329:
	s_waitcnt lgkmcnt(3)
	v_mfma_f32_16x16x32_bf16 v[168:171], v[78:81], v[18:21], v[90:93]
	s_waitcnt lgkmcnt(1)
	v_mfma_f32_16x16x32_bf16 v[172:175], v[86:89], v[18:21], v[94:97]
	v_exp_f32_e32 v145, v74
	v_exp_f32_e32 v146, v75
	v_exp_f32_e32 v147, v76
	v_exp_f32_e32 v148, v77
	ds_read_b128 v[176:179], v131 offset:61440
	v_mfma_f32_16x16x32_bf16 v[58:61], v[220:223], v[14:17], v[58:61]
	ds_read_b128 v[78:81], v131 offset:54272
	v_max3_f32 v195, v160, v161, v162
	v_max3_f32 v195, v195, v163, v164
	v_max3_f32 v195, v195, v165, v166
	v_max_f32_e32 v195, v195, v167
	ds_read_b128 v[82:85], v131 offset:63488
	s_waitcnt lgkmcnt(3)
	v_mfma_f32_16x16x32_bf16 v[54:57], v[140:143], v[14:17], v[54:57]
	ds_read_b128 v[86:89], v131 offset:56320
	s_cmp_ge_u32 s73, s71
	s_cbranch_scc1 .Latt_stgA_skip
	s_mul_hi_u32 s49, s50, 0xaaaaaaab
	s_lshr_b32 s49, s49, 1
	s_mul_i32 s49, s49, 0xc000
	s_sub_i32 s49, s31, s49
	s_add_i32 s49, s36, s49
	s_add_i32 s49, s2, s49
	s_lshl_b32 s51, s37, 14
	s_add_i32 s51, s76, s51
	s_mov_b32 m0, s49
	s_add_i32 s50, s51, 0xc000
	global_load_lds_dwordx4 v[114:115], off
	v_lshl_add_u64 v[192:193], v[114:115], 0, s[44:45]
	s_add_i32 m0, s49, 0x2000
	s_nop 0
	global_load_lds_dwordx4 v[192:193], off
	s_mov_b32 m0, s50
	s_nop 0
	global_load_lds_dwordx4 v[118:119], off
	s_add_i32 m0, s51, 0xe000
	s_nop 0
	global_load_lds_dwordx4 v[116:117], off

.Latt_B_1326:
	s_mul_hi_u32 s34, s77, 0xaaaaaaab
	s_lshr_b32 s34, s34, 1
	s_mul_i32 s34, s34, 0xc000
	v_subrev_u32_e32 v0, s34, v130
	s_add_i32 s34, s2, s36
	v_add_u32_e32 v0, s34, v0
	ds_read_b128 v[188:191], v0
	ds_read_b128 v[82:85], v0 offset:4096
	ds_read_b128 v[94:97], v0 offset:6144
	ds_read_b128 v[98:101], v0 offset:1024
	ds_read_b128 v[86:89], v0 offset:2048
	ds_read_b128 v[132:135], v0 offset:3072
	s_waitcnt lgkmcnt(9)
	v_mfma_f32_16x16x32_bf16 v[30:33], v[204:207], v[14:17], v[30:33]
	s_waitcnt lgkmcnt(8)
	v_mfma_f32_16x16x32_bf16 v[50:53], v[208:211], v[14:17], v[50:53]
	s_waitcnt lgkmcnt(7)
	v_mfma_f32_16x16x32_bf16 v[42:45], v[212:215], v[14:17], v[42:45]
	s_waitcnt lgkmcnt(6)
	v_mfma_f32_16x16x32_bf16 v[34:37], v[216:219], v[14:17], v[34:37]
	s_waitcnt lgkmcnt(5)
	v_mfma_f32_16x16x32_bf16 v[188:191], v[188:191], v[10:13], v[150:153]
	ds_read_b128 v[78:81], v0 offset:5120
	ds_read_b128 v[220:223], v131 offset:57344
	s_waitcnt lgkmcnt(3)
	v_mfma_f32_16x16x32_bf16 v[136:139], v[86:89], v[10:13], v[150:153]
	ds_read_b128 v[86:89], v0 offset:7168
	ds_read_b128 v[140:143], v131 offset:59392
	v_mfma_f32_16x16x32_bf16 v[90:93], v[82:85], v[10:13], v[150:153]
	v_mfma_f32_16x16x32_bf16 v[94:97], v[94:97], v[10:13], v[150:153]
	v_mfma_f32_16x16x32_bf16 v[74:77], v[98:101], v[18:21], v[188:191]
	s_waitcnt lgkmcnt(4)
	v_mfma_f32_16x16x32_bf16 v[70:73], v[132:135], v[18:21], v[136:139]
	s_mov_b32 s34, 0x41000000
	v_cmp_lt_f32_e32 vcc, s34, v194
	s_cmp_lg_u64 vcc, 0
	s_cselect_b64 s[34:35], -1, 0
	s_cbranch_vccz .Latt_B_1328
	v_cndmask_b32_e32 v132, 0, v194, vcc
	v_exp_f32_e64 v0, -v132
	v_sub_f32_e32 v160, v160, v132
	v_sub_f32_e32 v161, v161, v132
	v_sub_f32_e32 v162, v162, v132
	v_sub_f32_e32 v163, v163, v132
	v_sub_f32_e32 v164, v164, v132
	v_sub_f32_e32 v165, v165, v132
	v_sub_f32_e32 v166, v166, v132
	v_sub_f32_e32 v167, v167, v132
	v_sub_f32_e32 v168, v168, v132
	v_sub_f32_e32 v169, v169, v132
	v_sub_f32_e32 v170, v170, v132
	v_sub_f32_e32 v171, v171, v132
	v_sub_f32_e32 v172, v172, v132
	v_sub_f32_e32 v173, v173, v132
	v_sub_f32_e32 v174, v174, v132
	v_sub_f32_e32 v175, v175, v132
	v_add_f32_e32 v113, v113, v132
	v_xor_b32_e32 v150, 0x80000000, v113
	v_mov_b32_e32 v151, v150
	v_mov_b32_e32 v152, v150
	v_mov_b32_e32 v153, v150
	s_branch .Latt_B_1329
.Latt_B_1328:
.Latt_B_1329:
	s_waitcnt lgkmcnt(3)
	v_mfma_f32_16x16x32_bf16 v[22:25], v[78:81], v[18:21], v[90:93]
	s_waitcnt lgkmcnt(1)
	v_mfma_f32_16x16x32_bf16 v[26:29], v[86:89], v[18:21], v[94:97]
	v_exp_f32_e32 v145, v160
	v_exp_f32_e32 v146, v161
	v_exp_f32_e32 v147, v162
	v_exp_f32_e32 v148, v163
	ds_read_b128 v[176:179], v131 offset:61440
	v_mfma_f32_16x16x32_bf16 v[58:61], v[220:223], v[14:17], v[58:61]
	ds_read_b128 v[78:81], v131 offset:54272
	v_max3_f32 v195, v74, v75, v76
	v_max3_f32 v195, v195, v77, v70
	v_max3_f32 v195, v195, v71, v72
	v_max_f32_e32 v195, v195, v73
	ds_read_b128 v[82:85], v131 offset:63488
	s_waitcnt lgkmcnt(3)
	v_mfma_f32_16x16x32_bf16 v[54:57], v[140:143], v[14:17], v[54:57]
	ds_read_b128 v[86:89], v131 offset:56320
	s_cmp_ge_u32 s73, s71
	s_cbranch_scc1 .Latt_stgB_skip
	s_mul_hi_u32 s49, s50, 0xaaaaaaab
	s_lshr_b32 s49, s49, 1
	s_mul_i32 s49, s49, 0xc000
	s_sub_i32 s49, s31, s49
	s_add_i32 s49, s36, s49
	s_add_i32 s49, s2, s49
	s_lshl_b32 s51, s37, 14
	s_add_i32 s51, s76, s51
	s_mov_b32 m0, s49
	s_add_i32 s50, s51, 0xc000
	global_load_lds_dwordx4 v[114:115], off
	v_lshl_add_u64 v[192:193], v[114:115], 0, s[44:45]
	s_add_i32 m0, s49, 0x2000
	s_nop 0
	global_load_lds_dwordx4 v[192:193], off
	s_mov_b32 m0, s50
	s_nop 0
	global_load_lds_dwordx4 v[118:119], off
	s_add_i32 m0, s51, 0xe000
	s_nop 0
	global_load_lds_dwordx4 v[116:117], off
